# census rank kept in a spare VGPR and parked in LDS at the first barrier: thread 0 no longer waits for the arrival atomic at kernel start
# baseline (speedup 1.0000x reference)
; #define LAS __attribute__((address_space(3)))
; __device__ __forceinline__ unsigned xb_add(unsigned* p, unsigned v) { return __hip_atomic_fetch_add(p, v, __ATOMIC_RELAXED, __HIP_MEMORY_SCOPE_AGENT); }
; __device__ __forceinline__ unsigned xb_xcc_id() { return (unsigned)__builtin_amdgcn_s_getreg((3 << 11) | 20) & 0xFu; }
; __device__ __forceinline__ XcdBarrier xcd_barrier_post(unsigned* bar, volatile LAS unsigned* st) {
;     XcdBarrier b; b.bar = bar; b.x = xb_xcc_id(); b.st = st;
;     if (threadIdx.x == 0) (void)xb_add(&bar[XB_XCNT(b.x)], 1u);
; __global__ void __launch_bounds__(NTHREADS, 2) mk_fwd(Args a) {
;     ...
;     const int tid = threadIdx.x, lane = tid & 63, wave = __builtin_amdgcn_readfirstlane(tid >> 6);
;     unsigned char* ws = a.ws;
;     const int G = gridDim.x, c = blockIdx.x;
;     volatile LAS unsigned* MISC = (volatile LAS unsigned*)(lds + MISC_OFF);
;     if (tid < 32) MISC[tid] = 0u;
;     __syncthreads();
;     unsigned* barw = (unsigned*)(ws + WS_BAR);
;     XcdBarrier bar = xcd_barrier_post(barw, MISC + 8);
_Z6mk_fwd4Args:
	s_load_dwordx16 s[44:59], s[0:1], 0x80
	s_load_dword s97, s[0:1], 0xd0
	s_load_dwordx2 s[92:93], s[0:1], 0xc8
	s_add_u32 s6, s0, 0xc8
	v_and_b32_e32 v224, 0x3ff, v0
	s_addc_u32 s7, s1, 0
	v_readfirstlane_b32 s41, v224
	v_cmp_gt_u32_e32 vcc, 32, v224
	s_and_saveexec_b64 s[4:5], vcc
	v_lshl_add_u32 v1, v224, 2, 0
	v_add_u32_e32 v1, 0x23f00, v1
	v_mov_b32_e32 v2, 0
	ds_write_b32 v1, v2
	s_or_b64 exec, exec, s[4:5]
	s_load_dwordx2 s[4:5], s[0:1], 0xc0
	s_waitcnt lgkmcnt(0)
	s_barrier
	s_add_u32 s94, s58, 0xc0000
	s_getreg_b32 s3, hwreg(HW_REG_XCC_ID, 0, 4)
	s_addc_u32 s95, s59, 0
	s_and_b32 s3, s3, 15
	v_cmp_eq_u32_e64 s[24:25], 0, v224
	s_and_saveexec_b64 s[8:9], s[24:25]
	s_cbranch_execz .LBB0_5
	s_mov_b64 s[10:11], exec
	v_mbcnt_lo_u32_b32 v1, s10, 0
	v_mbcnt_hi_u32_b32 v1, s11, v1
	v_cmp_eq_u32_e32 vcc, 0, v1
	s_and_b64 s[12:13], exec, vcc
	s_mov_b64 exec, s[12:13]
	s_cbranch_execz .LBB0_5
	s_lshl_b32 s12, s3, 8
	s_bcnt1_i32_b64 s10, s[10:11]
	v_mov_b32_e32 v1, s12
	v_mov_b32_e32 v2, s10
	global_atomic_add v255, v1, v2, s[94:95] offset:1024 sc0

; __device__ __forceinline__ unsigned xb_ld(unsigned* p)              { return __hip_atomic_load(p, __ATOMIC_RELAXED, __HIP_MEMORY_SCOPE_AGENT); }
; __device__ __forceinline__ void xcd_barrier_complete(unsigned* bar, unsigned x, unsigned& nloc, unsigned& nx) {
;     ...
;         for (unsigned j = 0; j < 16; ++j) { const unsigned c = xb_ld(&bar[XB_XCNT(j)]); sum += c; cnt += (c > 0u) ? 1u : 0u; mine = (j == x) ? c : mine; }
;         if (sum == G) break;
;         __builtin_amdgcn_s_sleep(1);
;         if ((++sp & 255u) == 0u) { if (xb_ld(&bar[XB_TMO])) break; if (sp > XB_SPIN_CAP) { atomicAdd(&bar[XB_TMO], 1u); break; } }
;     }
;     nloc = mine > 0u ? mine : 1u; nx = cnt > 0u ? cnt : 1u;
; }
; __device__ __forceinline__ void xcd_barrier(const XcdBarrier& b) {
;     asm volatile("s_waitcnt vmcnt(0)" ::: "memory");
;     __syncthreads();
;     if (threadIdx.x == 0) {
;         unsigned* bar = b.bar;
;         __builtin_amdgcn_s_waitcnt(0);
;         unsigned nloc = b.st[0], nx = b.st[1];
;         if (nloc == 0u) { xcd_barrier_complete(bar, b.x, nloc, nx); b.st[0] = nloc; b.st[1] = nx; }
.LBB0_120:
	v_min_u32_e32 v17, v15, v0
	v_min3_u32 v17, v17, v1, v2
	v_min3_u32 v17, v17, v3, v4
	v_min3_u32 v17, v17, v5, v6
	s_cmp_eq_u32 s3, 0
	s_cselect_b64 vcc, -1, 0
	s_cmp_eq_u32 s3, 1
	v_cndmask_b32_e32 v16, 0, v15, vcc
	s_cselect_b64 vcc, -1, 0
	s_cmp_eq_u32 s3, 2
	v_cndmask_b32_e32 v16, v16, v0, vcc
	s_cselect_b64 vcc, -1, 0
	s_cmp_eq_u32 s3, 3
	v_cndmask_b32_e32 v16, v16, v1, vcc
	s_cselect_b64 vcc, -1, 0
	s_cmp_eq_u32 s3, 4
	v_cndmask_b32_e32 v16, v16, v2, vcc
	s_cselect_b64 vcc, -1, 0
	s_cmp_eq_u32 s3, 5
	v_cndmask_b32_e32 v16, v16, v3, vcc
	s_cselect_b64 vcc, -1, 0
	s_cmp_eq_u32 s3, 6
	v_cndmask_b32_e32 v16, v16, v4, vcc
	s_cselect_b64 vcc, -1, 0
	s_cmp_eq_u32 s3, 7
	v_cndmask_b32_e32 v16, v16, v5, vcc
	s_cselect_b64 vcc, -1, 0
	s_cmp_eq_u32 s3, 8
	v_cndmask_b32_e32 v16, v16, v6, vcc
	s_cselect_b64 vcc, -1, 0
	s_cmp_eq_u32 s3, 9
	v_cndmask_b32_e32 v16, v16, v7, vcc
	s_cselect_b64 vcc, -1, 0
	s_cmp_eq_u32 s3, 10
	v_cndmask_b32_e32 v16, v16, v8, vcc
	s_cselect_b64 vcc, -1, 0
	s_cmp_eq_u32 s3, 11
	v_cndmask_b32_e32 v16, v16, v9, vcc
	s_cselect_b64 vcc, -1, 0
	s_cmp_eq_u32 s3, 12
	v_cndmask_b32_e32 v16, v16, v10, vcc
	s_cselect_b64 vcc, -1, 0
	s_cmp_eq_u32 s3, 13
	v_cndmask_b32_e32 v16, v16, v11, vcc
	s_cselect_b64 vcc, -1, 0
	s_cmp_eq_u32 s3, 14
	v_cndmask_b32_e32 v16, v16, v12, vcc
	s_cselect_b64 vcc, -1, 0
	s_cmp_eq_u32 s3, 15
	v_cndmask_b32_e32 v16, v16, v13, vcc
	s_cselect_b64 vcc, -1, 0
	v_cndmask_b32_e32 v16, v16, v14, vcc
	v_cmp_ne_u32_e32 vcc, 0, v15
	s_add_i32 s4, 0, 0x23f20
	s_nop 0
	v_cndmask_b32_e64 v15, 0, 1, vcc
	v_cmp_ne_u32_e32 vcc, 0, v0
	s_nop 1
	v_addc_co_u32_e32 v0, vcc, 0, v15, vcc
	v_cmp_ne_u32_e32 vcc, 0, v1
	s_nop 1
	v_cndmask_b32_e64 v1, 0, 1, vcc
	v_cmp_ne_u32_e32 vcc, 0, v2
	v_max_u32_e32 v2, 1, v16
	s_nop 0
	v_addc_co_u32_e32 v0, vcc, v0, v1, vcc
	v_cmp_ne_u32_e32 vcc, 0, v3
	s_nop 1
	v_cndmask_b32_e64 v1, 0, 1, vcc
	v_cmp_ne_u32_e32 vcc, 0, v4
	s_nop 1
	v_addc_co_u32_e32 v0, vcc, v0, v1, vcc
	v_cmp_ne_u32_e32 vcc, 0, v5
	s_nop 1
	v_cndmask_b32_e64 v1, 0, 1, vcc
	v_cmp_ne_u32_e32 vcc, 0, v6
	s_nop 1
	v_addc_co_u32_e32 v0, vcc, v0, v1, vcc
	v_cmp_ne_u32_e32 vcc, 0, v7
	s_nop 1
	v_cndmask_b32_e64 v1, 0, 1, vcc
	v_cmp_ne_u32_e32 vcc, 0, v8
	s_nop 1
	v_addc_co_u32_e32 v0, vcc, v0, v1, vcc
	v_cmp_ne_u32_e32 vcc, 0, v9
	s_nop 1
	v_cndmask_b32_e64 v1, 0, 1, vcc
	v_cmp_ne_u32_e32 vcc, 0, v10
	s_nop 1
	v_addc_co_u32_e32 v0, vcc, v0, v1, vcc
	v_cmp_ne_u32_e32 vcc, 0, v11
	s_nop 1
	v_cndmask_b32_e64 v1, 0, 1, vcc
	v_cmp_ne_u32_e32 vcc, 0, v12
	s_nop 1
	v_addc_co_u32_e32 v0, vcc, v0, v1, vcc
	v_cmp_ne_u32_e32 vcc, 0, v13
	s_nop 1
	v_cndmask_b32_e64 v1, 0, 1, vcc
	v_cmp_ne_u32_e32 vcc, 0, v14
	s_nop 1
	v_addc_co_u32_e32 v0, vcc, v0, v1, vcc
	v_mov_b32_e32 v1, s4
	s_add_i32 s4, 0, 0x23f24
	v_max_u32_e32 v0, 1, v0
	ds_write_b32 v1, v2
	v_mov_b32_e32 v1, s4
	ds_write_b32 v1, v0
	v_cmp_eq_u32_e32 vcc, 32, v17
	s_cmp_eq_u32 s39, 0x100
	s_cselect_b64 s[48:49], -1, 0
	s_nop 3
	s_and_b64 vcc, vcc, s[48:49]
	s_nop 3
	v_cndmask_b32_e64 v17, 0, 1, vcc
	v_mov_b32_e32 v16, 0x23f34
	ds_write_b32 v16, v17
	v_mov_b32_e32 v16, 0x23f30
	ds_write_b32 v16, v255
